# job dequeue atomics (attention and sparse phases) issued before the workgroup barrier that precedes them
# speedup vs baseline: 1.0116x; 1.0035x over previous
; DI int next_job(u32* ctr, unsigned char* smem) {
;   int* sj = (int*)(smem + SJOB_OFF);
;   __syncthreads();
;   if (threadIdx.x == 0) *sj = (int)atomicAdd(ctr, 1u);
;   __syncthreads();
;   return *sj;
; }
; DI void phase_sparse(const Params& p, int layer, int phase, unsigned char* smem) {
;     ...
;   for (;;) {
;     const int jp = next_job(ctr, smem);
;     if (jp >= 528) break;
.LBB0_308:
	s_mov_b64 s[2:3], exec
	v_readlane_b32 s4, v253, 1
	v_readlane_b32 s5, v253, 2
	s_and_b64 s[4:5], s[2:3], s[4:5]
	s_mov_b64 exec, s[4:5]
	s_cbranch_execz .Lsq_pre
	v_readlane_b32 s6, v252, 32
	v_readlane_b32 s7, v252, 33
	v_mov_b32_e32 v2, 1
	s_nop 3
	global_atomic_add v2, v1, v2, s[6:7] sc0
.Lsq_pre:
	s_mov_b64 exec, s[2:3]
	s_barrier
	s_mov_b64 s[2:3], exec
	v_readlane_b32 s4, v253, 1
	v_readlane_b32 s5, v253, 2
	s_and_b64 s[4:5], s[2:3], s[4:5]
	s_mov_b64 exec, s[4:5]
	s_cbranch_execz .LBB0_312
	s_waitcnt vmcnt(0)
	v_mov_b32_e32 v0, v2
	ds_write_b32 v200, v0

; DI int next_job(u32* ctr, unsigned char* smem) {
;   int* sj = (int*)(smem + SJOB_OFF);
;   __syncthreads();
;   if (threadIdx.x == 0) *sj = (int)atomicAdd(ctr, 1u);
;   __syncthreads();
;   return *sj;
; }
; DI void phase_attn(const Params& p, int layer, int phase, unsigned char* smem) {
;     ...
;   for (;;) {
;     const int jp = next_job(ctr, smem);
;     if (jp >= 2640) break;
.LBB0_360:
	s_mov_b64 s[2:3], exec
	v_readlane_b32 s4, v253, 1
	v_readlane_b32 s5, v253, 2
	s_and_b64 s[4:5], s[2:3], s[4:5]
	s_mov_b64 exec, s[4:5]
	s_cbranch_execz .Lxq_pre
	v_readlane_b32 s6, v252, 62
	v_readlane_b32 s7, v252, 61
	s_nop 0
	s_cmp_lt_u32 s7, 8
	s_cbranch_scc0 .Lxq_pre
	s_lshl_b32 s4, s6, 2
	s_add_u32 s4, s52, s4
	s_addc_u32 s5, s53, 0
	v_mov_b32_e32 v2, 1
	global_atomic_add v2, v1, v2, s[4:5] sc0
.Lxq_pre:
	s_mov_b64 exec, s[2:3]
	s_barrier
	s_mov_b64 s[2:3], exec
	v_readlane_b32 s4, v253, 1
	v_readlane_b32 s5, v253, 2
	s_and_b64 s[4:5], s[2:3], s[4:5]
	s_mov_b64 exec, s[4:5]
	s_cbranch_execz .LBB0_364
	v_readlane_b32 s6, v252, 62
	v_readlane_b32 s7, v252, 61
	s_nop 0
	s_cmp_lt_u32 s7, 8
	s_cbranch_scc0 .Lxq_done
	s_branch .Lxq_wait

; DI int next_job(u32* ctr, unsigned char* smem) {
;   int* sj = (int*)(smem + SJOB_OFF);
;   __syncthreads();
;   if (threadIdx.x == 0) *sj = (int)atomicAdd(ctr, 1u);
;   __syncthreads();
;   return *sj;
; }
.Lxq_wait:
	s_waitcnt vmcnt(0)
	v_readfirstlane_b32 s10, v2
	s_nop 0
	s_cmpk_lt_u32 s10, 0x14a
	s_cbranch_scc1 .Lxq_got
	s_add_i32 s6, s6, 1
	s_and_b32 s6, s6, 7
	s_add_i32 s7, s7, 1
	s_branch .Lxq_loop
